# speedup vs baseline: 1.0134x; 1.0051x over previous
; __device__ __forceinline__ int mytid(int wv) { return (wv << 6) | (int)__builtin_amdgcn_mbcnt_hi(~0u, __builtin_amdgcn_mbcnt_lo(~0u, 0u)); }
; __device__ __forceinline__ unsigned short f2bf(float x) { return (unsigned short)(cvtpk(x, x) & 0xffffu); }
; #define p getp()
; __device__ __forceinline__ void phase_mla_norm(KP p, int wv) {
;     ...
;   int tid = mytid(wv); asm volatile("" : "+v"(tid));
;   const int wid = tid >> 6, lane = tid & 63;
;   for (int t = blockIdx.x * 8 + wid; t < TOK; t += gridDim.x * 8) {
;     const float* d = dn + (long)t * NDN;
;     float a[6], c[8];
; #pragma unroll
;     for (int i = 0; i < 6; ++i) a[i] = d[i * 64 + lane];
; #pragma unroll
;     for (int i = 0; i < 8; ++i) c[i] = d[384 + i * 64 + lane];
;     const float kr = d[896 + lane];
;     float sa = 0.f, sc = 0.f;
; #pragma unroll
;     for (int i = 0; i < 6; ++i) sa += a[i] * a[i];
; #pragma unroll
;     for (int i = 0; i < 8; ++i) sc += c[i] * c[i];
;     sa = wave_sum(sa); sc = wave_sum(sc);
;     const float ra = rsqrtf(sa * (1.f / RQ) + 1e-6f), rc = rsqrtf(sc * (1.f / RKV) + 1e-6f);
; #pragma unroll
;     for (int i = 0; i < 6; ++i) cq[(long)t * RQ + i * 64 + lane] = f2bf(a[i] * ra * p->mla_g_q[i * 64 + lane]);
; #pragma unroll
;     for (int i = 0; i < 8; ++i) ckv[(long)t * RKV + i * 64 + lane] = f2bf(c[i] * rc * p->mla_g_kv[i * 64 + lane]);
;     const float other = __shfl_xor(kr, 32);
;     const float cs = P_ropeC[(t & (SEQ - 1)) * 32 + (lane & 31)], sn = P_ropeS[(t & (SEQ - 1)) * 32 + (lane & 31)];
.LBB0_760:
	s_or_b64 exec, exec, s[6:7]
	s_mov_b64 s[8:9], s[90:91]
	v_mov_b32_e32 v6, v192
	s_barrier
	v_readlane_b32 s0, v255, 8
	v_ashrrev_i32_e32 v1, 6, v6
	s_nop 0
	v_add_u32_e32 v0, s0, v1
	s_mov_b32 s0, 0xc000
	v_cmp_gt_i32_e32 vcc, s0, v0
	s_and_saveexec_b64 s[10:11], vcc
	s_cbranch_execz .LBB0_763
	v_and_b32_e32 v2, 64, v200
	v_add_u32_e32 v2, 64, v2
	v_cmp_lt_i32_e32 vcc, v206, v2
	s_load_dwordx2 s[2:3], s[8:9], 0xa8
	s_load_dwordx2 s[0:1], s[8:9], 0x50
	v_cndmask_b32_e32 v3, v200, v206, vcc
	v_lshlrev_b32_e32 v13, 2, v3
	v_xor_b32_e32 v3, 16, v200
	v_cmp_lt_i32_e32 vcc, v3, v2
	v_and_b32_e32 v14, 63, v6
	v_mov_b32_e32 v15, 0
	v_cndmask_b32_e32 v3, v200, v3, vcc
	v_lshlrev_b32_e32 v16, 2, v3
	v_xor_b32_e32 v3, 8, v200
	v_cmp_lt_i32_e32 vcc, v3, v2
	s_waitcnt lgkmcnt(0)
	s_add_u32 s12, s2, 0xb640000
	s_mov_b64 s[6:7], 0x20a40000
	v_cndmask_b32_e32 v3, v200, v3, vcc
	v_lshlrev_b32_e32 v17, 2, v3
	v_xor_b32_e32 v3, 4, v200
	v_cmp_lt_i32_e32 vcc, v3, v2
	s_addc_u32 s13, s3, 0
	s_add_u32 s14, s2, 0xb840000
	v_cndmask_b32_e32 v3, v200, v3, vcc
	v_cmp_lt_i32_e32 vcc, v201, v2
	v_lshlrev_b32_e32 v18, 2, v3
	v_lshlrev_b32_e32 v10, 2, v14
	v_cndmask_b32_e32 v3, v200, v201, vcc
	v_lshlrev_b32_e32 v19, 2, v3
	v_xor_b32_e32 v3, 1, v200
	v_cmp_lt_i32_e32 vcc, v3, v2
	v_mov_b32_e32 v11, v15
	v_and_b32_e32 v21, 31, v6
	v_cndmask_b32_e32 v2, v200, v3, vcc
	v_lshlrev_b32_e32 v20, 2, v2
	v_lshlrev_b32_e32 v2, 1, v14
	v_mov_b32_e32 v3, v15
	v_lshl_add_u64 v[4:5], s[2:3], 0, v[2:3]
	v_lshl_add_u64 v[2:3], v[4:5], 0, s[6:7]
	s_mov_b64 s[6:7], 0x22e40000
	v_lshl_add_u64 v[4:5], v[4:5], 0, s[6:7]
	s_addc_u32 s15, s3, 0
	v_lshl_add_u64 v[6:7], s[2:3], 0, v[14:15]
	s_mov_b64 s[6:7], 0x17a40080
	v_lshl_add_u64 v[8:9], s[0:1], 0, v[10:11]
	v_lshl_add_u64 v[10:11], s[2:3], 0, v[10:11]
	s_mov_b64 s[2:3], 0x2be40000
	v_lshlrev_b32_e32 v1, 5, v1
	s_mov_b32 s18, 0x3b000000
	v_cmp_gt_u32_e32 vcc, 32, v14
	v_lshl_add_u64 v[6:7], v[6:7], 0, s[6:7]
	s_lshl_b32 s0, s88, 3
	v_lshl_add_u64 v[10:11], v[10:11], 0, s[2:3]
	v_lshl_add_u32 v22, s89, 8, v1
	s_lshl_b32 s1, s88, 8
	s_mov_b64 s[16:17], 0
	s_mov_b32 s19, 0x3b2aaaab
	v_mov_b32_e32 v12, 0x358637bd
	s_mov_b32 s3, 0x800000
	s_movk_i32 s20, 0x300
	v_lshlrev_b32_e32 v23, 2, v14
	s_mov_b32 s21, 0x7ffe0
	s_movk_i32 s22, 0xc00
	s_mov_b32 s23, 0xbfff
	s_load_dwordx2 s[24:25], s[8:9], 0x68
	s_waitcnt lgkmcnt(0)
	global_load_dword v144, v[8:9], off offset:256
	global_load_dword v145, v[8:9], off offset:512
	global_load_dword v146, v[8:9], off offset:768
	global_load_dword v147, v[8:9], off offset:1024
	global_load_dword v148, v[8:9], off offset:1280
	global_load_dword v149, v23, s[24:25]
	global_load_dword v150, v23, s[24:25] offset:256
	global_load_dword v151, v23, s[24:25] offset:512
	global_load_dword v152, v23, s[24:25] offset:768
	global_load_dword v153, v23, s[24:25] offset:1024
	global_load_dword v154, v23, s[24:25] offset:1280
	global_load_dword v155, v23, s[24:25] offset:1536
	global_load_dword v156, v23, s[24:25] offset:1792
; __device__ __forceinline__ unsigned short f2bf(float x) { return (unsigned short)(cvtpk(x, x) & 0xffffu); }
; #define p getp()
; __device__ __forceinline__ void phase_mla_norm(KP p, int wv) {
;     ...
;   for (int t = blockIdx.x * 8 + wid; t < TOK; t += gridDim.x * 8) {
;     const float* d = dn + (long)t * NDN;
;     float a[6], c[8];
; #pragma unroll
;     for (int i = 0; i < 6; ++i) a[i] = d[i * 64 + lane];
; #pragma unroll
;     for (int i = 0; i < 8; ++i) c[i] = d[384 + i * 64 + lane];
;     const float kr = d[896 + lane];
;     float sa = 0.f, sc = 0.f;
; #pragma unroll
;     for (int i = 0; i < 6; ++i) sa += a[i] * a[i];
; #pragma unroll
;     for (int i = 0; i < 8; ++i) sc += c[i] * c[i];
;     sa = wave_sum(sa); sc = wave_sum(sc);
;     const float ra = rsqrtf(sa * (1.f / RQ) + 1e-6f), rc = rsqrtf(sc * (1.f / RKV) + 1e-6f);
; #pragma unroll
;     for (int i = 0; i < 6; ++i) cq[(long)t * RQ + i * 64 + lane] = f2bf(a[i] * ra * p->mla_g_q[i * 64 + lane]);
; #pragma unroll
;     for (int i = 0; i < 8; ++i) ckv[(long)t * RKV + i * 64 + lane] = f2bf(c[i] * rc * p->mla_g_kv[i * 64 + lane]);
;     const float other = __shfl_xor(kr, 32);
;     const float cs = P_ropeC[(t & (SEQ - 1)) * 32 + (lane & 31)], sn = P_ropeS[(t & (SEQ - 1)) * 32 + (lane & 31)];
;     const float out = (lane < 32) ? kr * cs - other * sn : other * sn + kr * cs;
;     const unsigned char ob = (unsigned char)(__builtin_amdgcn_cvt_pk_fp8_f32(out, out, 0, false) & 0xff);
; #pragma unroll
;     for (int h = 0; h < 16; ++h) K8[(long)t * NUQ + h * 192 + 128 + lane] = ob;
;   }
.LBB0_762:
	v_ashrrev_i32_e32 v1, 31, v0
	v_lshlrev_b64 v[14:15], 12, v[0:1]
	v_lshl_add_u64 v[24:25], v[10:11], 0, v[14:15]
	global_load_dword v48, v[24:25], off
	global_load_dword v27, v[24:25], off offset:256
	global_load_dword v28, v[24:25], off offset:512
	global_load_dword v29, v[24:25], off offset:768
	global_load_dword v30, v[24:25], off offset:1024
	global_load_dword v31, v[24:25], off offset:1280
	global_load_dword v32, v[24:25], off offset:1536
	global_load_dword v49, v[24:25], off offset:1792
	global_load_dword v33, v[24:25], off offset:2048
	global_load_dword v26, v[24:25], off offset:2304
	global_load_dword v34, v[24:25], off offset:2560
	global_load_dword v35, v[24:25], off offset:2816
	global_load_dword v14, v[24:25], off offset:3072
	global_load_dword v15, v[24:25], off offset:3328
	global_load_dword v50, v[8:9], off
	global_load_dword v51, v[24:25], off offset:3584
	s_waitcnt vmcnt(15)
	v_mul_f32_e32 v45, v48, v48
	s_waitcnt vmcnt(12)
	v_pk_mul_f32 v[24:25], v[28:29], v[28:29]
	s_nop 0
	v_mov_b32_e32 v47, v24
	s_waitcnt vmcnt(10)
	v_pk_mul_f32 v[36:37], v[30:31], v[30:31]
	s_waitcnt vmcnt(7)
	v_pk_mul_f32 v[38:39], v[32:33], v[32:33]
	s_nop 0
	v_fma_f32 v38, v49, v49, v38
	v_add_f32_e32 v44, v38, v39
	s_waitcnt vmcnt(4)
	v_pk_mul_f32 v[40:41], v[34:35], v[34:35]
	v_pk_fma_f32 v[38:39], v[26:27], v[26:27], v[44:45]
	v_mov_b32_e32 v46, v40
	s_waitcnt vmcnt(2)
	v_pk_mul_f32 v[42:43], v[14:15], v[14:15]
	v_mov_b32_e32 v24, v41
	v_pk_add_f32 v[38:39], v[38:39], v[46:47]
	v_mov_b32_e32 v40, v42
	v_mov_b32_e32 v41, v36
	v_pk_add_f32 v[24:25], v[38:39], v[24:25]
	v_mov_b32_e32 v36, v43
	v_pk_add_f32 v[24:25], v[24:25], v[40:41]
	s_nop 0
	v_pk_add_f32 v[24:25], v[24:25], v[36:37]
	ds_bpermute_b32 v37, v13, v25
	ds_bpermute_b32 v36, v13, v24
	s_waitcnt lgkmcnt(0)
	v_pk_add_f32 v[24:25], v[24:25], v[36:37]
	ds_bpermute_b32 v37, v16, v25
	ds_bpermute_b32 v36, v16, v24
	s_waitcnt lgkmcnt(0)
	v_pk_add_f32 v[24:25], v[24:25], v[36:37]
	ds_bpermute_b32 v37, v17, v25
	ds_bpermute_b32 v36, v17, v24
	s_waitcnt lgkmcnt(0)
	v_pk_add_f32 v[24:25], v[24:25], v[36:37]
	ds_bpermute_b32 v37, v18, v25
	ds_bpermute_b32 v36, v18, v24
	s_waitcnt lgkmcnt(0)
	v_pk_add_f32 v[24:25], v[24:25], v[36:37]
	ds_bpermute_b32 v37, v19, v25
	ds_bpermute_b32 v36, v19, v24
	s_waitcnt lgkmcnt(0)
	v_pk_add_f32 v[24:25], v[24:25], v[36:37]
	ds_bpermute_b32 v37, v20, v25
	ds_bpermute_b32 v36, v20, v24
	s_waitcnt lgkmcnt(0)
	v_pk_add_f32 v[24:25], v[24:25], v[36:37]
	s_nop 0
	v_pk_fma_f32 v[24:25], v[24:25], s[18:19], v[12:13] op_sel_hi:[1,1,0]
	s_nop 0
	v_mul_f32_e32 v36, 0x4b800000, v25
	v_cmp_gt_f32_e64 s[6:7], s3, v25
	s_nop 1
	v_cndmask_b32_e64 v25, v25, v36, s[6:7]
	v_rsq_f32_e32 v25, v25
	s_nop 0
	v_mul_f32_e32 v36, 0x45800000, v25
	v_cndmask_b32_e64 v25, v25, v36, s[6:7]
	v_mul_f32_e32 v36, v48, v25
	s_waitcnt vmcnt(0)
	v_mul_f32_e32 v36, v50, v36
	v_cvt_pk_bf16_f32 v38, v36, v36
	v_mul_f32_e32 v27, v27, v25
	v_mad_i64_i32 v[36:37], s[6:7], v0, s20, v[2:3]
	global_store_short v[36:37], v38, off
	v_mul_f32_e32 v28, v28, v25
	v_mul_f32_e32 v29, v29, v25
	v_cmp_gt_f32_e64 s[6:7], s3, v24
	v_mul_f32_e32 v27, v27, v144
	v_cvt_pk_bf16_f32 v27, v27, v27
	s_nop 0
	global_store_short v[36:37], v27, off offset:128
	v_mul_f32_e32 v27, v28, v145
	v_cvt_pk_bf16_f32 v27, v27, v27
	s_nop 0
	global_store_short v[36:37], v27, off offset:256
	v_mul_f32_e32 v27, v29, v146
	v_cvt_pk_bf16_f32 v27, v27, v27
	v_mul_f32_e32 v29, v30, v25
	global_store_short v[36:37], v27, off offset:384
	v_mul_f32_e32 v25, v31, v25
	v_mul_f32_e32 v27, v29, v147
	v_cvt_pk_bf16_f32 v27, v27, v27
	v_mul_f32_e32 v25, v25, v148
	global_store_short v[36:37], v27, off offset:512
	v_cvt_pk_bf16_f32 v25, v25, v25
	v_mul_f32_e32 v28, 0x4b800000, v24
	v_cndmask_b32_e64 v24, v24, v28, s[6:7]
	v_rsq_f32_e32 v24, v24
	global_store_short v[36:37], v25, off offset:640
	s_waitcnt lgkmcnt(0)
	v_mul_f32_e32 v28, 0x45800000, v24
	v_cndmask_b32_e64 v28, v24, v28, s[6:7]
	v_mul_f32_e32 v24, v32, v28
	v_mul_f32_e32 v26, v26, v28
	v_mul_f32_e32 v14, v14, v28
	v_mul_f32_e32 v15, v15, v28
	v_mul_f32_e32 v24, v24, v149
	v_cvt_pk_bf16_f32 v27, v24, v24
	v_lshlrev_b64 v[24:25], 10, v[0:1]
	v_mul_f32_e32 v1, v49, v28
	v_lshl_add_u64 v[24:25], v[4:5], 0, v[24:25]
	global_store_short v[24:25], v27, off
	v_mul_f32_e32 v1, v1, v150
	v_cvt_pk_bf16_f32 v1, v1, v1
	v_mul_f32_e32 v29, v33, v28
	global_store_short v[24:25], v1, off offset:128
	v_mul_f32_e32 v1, v29, v151
	v_cvt_pk_bf16_f32 v1, v1, v1
	ds_bpermute_b32 v29, v13, v51
	global_store_short v[24:25], v1, off offset:256
	v_mul_f32_e32 v1, v26, v152
	v_cvt_pk_bf16_f32 v1, v1, v1
	v_mul_f32_e32 v27, v34, v28
	global_store_short v[24:25], v1, off offset:384
	v_mul_f32_e32 v1, v27, v153
	v_cvt_pk_bf16_f32 v1, v1, v1
	v_mul_f32_e32 v27, v35, v28
	global_store_short v[24:25], v1, off offset:512
	v_mul_f32_e32 v1, v27, v154
	v_cvt_pk_bf16_f32 v1, v1, v1
	s_nop 0
	global_store_short v[24:25], v1, off offset:640
	v_mul_f32_e32 v1, v14, v155
	v_cvt_pk_bf16_f32 v1, v1, v1
	v_and_or_b32 v26, v22, s21, v21
	v_lshlrev_b32_e32 v26, 2, v26
	global_store_short v[24:25], v1, off offset:768
	v_add_u32_e32 v22, s1, v22
	v_mul_f32_e32 v1, v15, v156
	v_cvt_pk_bf16_f32 v1, v1, v1
	global_load_dword v27, v26, s[14:15]
	global_load_dword v28, v26, s[12:13]
	v_mov_b32_e32 v26, 0
	global_store_short v[24:25], v1, off offset:896
	v_mad_i64_i32 v[14:15], s[6:7], v0, s22, v[6:7]
	v_add_u32_e32 v0, s0, v0
	v_cmp_lt_i32_e64 s[6:7], s23, v0
	s_or_b64 s[16:17], s[6:7], s[16:17]
	s_waitcnt vmcnt(2) lgkmcnt(0)
	v_mul_f32_e32 v1, v27, v29
	v_cndmask_b32_e64 v1, v1, -v1, vcc
	s_waitcnt vmcnt(1)
	v_fmac_f32_e32 v1, v51, v28
	v_cvt_pk_fp8_f32 v26, v1, v1
	global_store_byte v[14:15], v26, off
	global_store_byte v[14:15], v26, off offset:192
	global_store_byte v[14:15], v26, off offset:384
	global_store_byte v[14:15], v26, off offset:576
	global_store_byte v[14:15], v26, off offset:768
	global_store_byte v[14:15], v26, off offset:960
	global_store_byte v[14:15], v26, off offset:1152
	global_store_byte v[14:15], v26, off offset:1344
	global_store_byte v[14:15], v26, off offset:1536
	global_store_byte v[14:15], v26, off offset:1728
	global_store_byte v[14:15], v26, off offset:1920
	global_store_byte v[14:15], v26, off offset:2112
	global_store_byte v[14:15], v26, off offset:2304
	global_store_byte v[14:15], v26, off offset:2496
	global_store_byte v[14:15], v26, off offset:2688
	global_store_byte v[14:15], v26, off offset:2880
	s_andn2_b64 exec, exec, s[16:17]
	s_cbranch_execnz .LBB0_762
